# FFN-down epilogues: the 8 gate loads of each 32-row group issued together and waited once (was 32 serial load/wait round trips per tile)
# baseline (speedup 1.0000x reference)
; DI f32x16 mfma32(bf16x8 a, bf16x8 b, f32x16 c) { return __builtin_amdgcn_mfma_f32_32x32x16_bf16(a, b, c, 0, 0, 0); }
; DI s16x4 tr_read(const char* p) { bfx4 r = __builtin_amdgcn_ds_read_tr16_b64_v4bf16((LDS_AS bfx4*)p); return __builtin_bit_cast(s16x4, r); }
; DI bf16x8 cat8(s16x4 lo, s16x4 hi) { return __builtin_shufflevector(lo, hi, 0, 1, 2, 3, 4, 5, 6, 7); }
; template <int BM, class Epi>
; DI void gemm_tile(const bf16_t* __restrict__ A, int lda, const bf16_t* __restrict__ B, int ldb, int K, int row0, int col0, const Epi& epi, char* smem) {
;     ...
;     for (int kt = 0; kt < nk; ++kt) {
;         const char* cur = smem + (kt & 1) * GSTAGE;
;         char* nxt = smem + ((kt & 1) ^ 1) * GSTAGE;
;         const bool w1 = kt + 1 < nk, l2 = kt + 2 < nk;
;         const bf16_t* a2 = ag + (size_t)(kt + 2) * 64; const bf16_t* b2 = bg + (size_t)(kt + 2) * 64 * ldb;
; #pragma unroll
;         for (int s = 0; s < 4; ++s) {
;             bf16x8 xf[MI], wf[2];
; #pragma unroll
;             for (int mi = 0; mi < MI; ++mi) xf[mi] = *(const bf16x8*)(cur + xoff + mi * 32 * GA_S + s * 32);
; #pragma unroll
;             for (int ni = 0; ni < 2; ++ni) {
;                 const char* wp = cur + woff + s * 16 * GB_S + ni * 64;
;                 wf[ni] = cat8(tr_read(wp), tr_read(wp + 4 * GB_S));
;             }
; #pragma unroll
;             for (int mi = 0; mi < MI; ++mi)
; #pragma unroll
;                 for (int ni = 0; ni < 2; ++ni) acc[mi][ni] = mfma32(wf[ni], xf[mi], acc[mi][ni]);
;             if (w1) {
;                 if (s < NA_) *(u32x4*)(nxt + aw + 64 * s * GA_S) = ra[s];
;                 *(u32x4*)(nxt + bw + 16 * s * GB_S) = rb[s];
;             }
;             if (l2) {
;                 if (s < NA_) ra[s] = *(const u32x4*)(a2 + (size_t)(64 * s) * lda);
;                 rb[s] = *(const u32x4*)(b2 + (size_t)(16 * s) * ldb);
;             }
;         }
;         __syncthreads();
;     }
.Lmy_g_mid:
	ds_read_b128 v[218:221], v165 offset:9216
	ds_read_b128 v[222:225], v165 offset:13824
	v_add_u32_e32 v192, s17, v168
	v_add_u32_e32 v193, s18, v170
	v_add_u32_e32 v226, s19, v168
	v_add_u32_e32 v227, s20, v170
	v_add_u32_e32 v228, s21, v168
	v_add_u32_e32 v229, s22, v170
	v_add_u32_e32 v230, s23, v168
	v_add_u32_e32 v231, s24, v170
	v_lshl_add_u64 v[170:171], v[170:171], 0, s[28:29]
	v_lshl_add_u64 v[168:169], v[168:169], 0, s[26:27]
	s_add_i32 s11, s11, 1
	s_waitcnt lgkmcnt(5)
	v_mfma_f32_32x32x16_bf16 v[112:127], v[234:237], v[184:187], v[112:127]
	ds_read_b64_tr_b16 v[242:243], v172 offset:46080
	ds_read_b64_tr_b16 v[244:245], v172 offset:48384
	ds_read_b64_tr_b16 v[246:247], v172 offset:46144
	ds_read_b64_tr_b16 v[248:249], v172 offset:48448
	s_waitcnt lgkmcnt(7)
	v_mfma_f32_32x32x16_bf16 v[96:111], v[238:241], v[184:187], v[96:111]
	ds_read_b128 v[184:187], v165 offset:32
	s_waitcnt lgkmcnt(7)
	v_mfma_f32_32x32x16_bf16 v[80:95], v[234:237], v[188:191], v[80:95]
	v_mfma_f32_32x32x16_bf16 v[64:79], v[238:241], v[188:191], v[64:79]
	ds_read_b128 v[188:191], v165 offset:4640
	s_waitcnt vmcnt(7)
	ds_write_b128 v217, v[152:155]
	s_waitcnt vmcnt(6)
	ds_write_b128 v232, v[156:159] offset:36864
	global_load_dwordx4 v[152:155], v192, s[94:95] offset:768
	global_load_dwordx4 v[156:159], v193, s[94:95]
	s_waitcnt lgkmcnt(9)
	v_mfma_f32_32x32x16_bf16 v[48:63], v[234:237], v[218:221], v[48:63]
	v_mfma_f32_32x32x16_bf16 v[32:47], v[238:241], v[218:221], v[32:47]
	ds_read_b128 v[218:221], v165 offset:9248
	s_waitcnt lgkmcnt(9)
	v_mfma_f32_32x32x16_bf16 v[16:31], v[234:237], v[222:225], v[16:31]
	v_mfma_f32_32x32x16_bf16 v[0:15], v[238:241], v[222:225], v[0:15]
	ds_read_b128 v[222:225], v165 offset:13856
	s_waitcnt vmcnt(7)
	ds_write_b128 v217, v[144:147] offset:9216
	s_waitcnt vmcnt(6)
	ds_write_b128 v232, v[148:151] offset:46080
	global_load_dwordx4 v[144:147], v226, s[94:95] offset:768
	global_load_dwordx4 v[148:151], v227, s[94:95]
	s_waitcnt lgkmcnt(7)
	v_mfma_f32_32x32x16_bf16 v[112:127], v[242:245], v[184:187], v[112:127]
	ds_read_b64_tr_b16 v[234:235], v172 offset:55296
	ds_read_b64_tr_b16 v[236:237], v172 offset:57600
	ds_read_b64_tr_b16 v[238:239], v172 offset:55360
	ds_read_b64_tr_b16 v[240:241], v172 offset:57664
	v_mfma_f32_32x32x16_bf16 v[96:111], v[246:249], v[184:187], v[96:111]
	ds_read_b128 v[184:187], v165 offset:64
	s_waitcnt lgkmcnt(11)
	v_mfma_f32_32x32x16_bf16 v[80:95], v[242:245], v[188:191], v[80:95]
	v_mfma_f32_32x32x16_bf16 v[64:79], v[246:249], v[188:191], v[64:79]
	ds_read_b128 v[188:191], v165 offset:4672
	s_waitcnt vmcnt(7)
	ds_write_b128 v217, v[136:139] offset:18432
	s_waitcnt vmcnt(6)
	ds_write_b128 v232, v[140:143] offset:55296
	global_load_dwordx4 v[136:139], v228, s[94:95] offset:768
	global_load_dwordx4 v[140:143], v229, s[94:95]
	s_waitcnt lgkmcnt(11)
	v_mfma_f32_32x32x16_bf16 v[48:63], v[242:245], v[218:221], v[48:63]
	v_mfma_f32_32x32x16_bf16 v[32:47], v[246:249], v[218:221], v[32:47]
	ds_read_b128 v[218:221], v165 offset:9280
	s_waitcnt lgkmcnt(11)
	v_mfma_f32_32x32x16_bf16 v[16:31], v[242:245], v[222:225], v[16:31]
	v_mfma_f32_32x32x16_bf16 v[0:15], v[246:249], v[222:225], v[0:15]
	ds_read_b128 v[222:225], v165 offset:13888
	s_waitcnt vmcnt(7)
	ds_write_b128 v217, v[128:131] offset:27648
	s_waitcnt vmcnt(6)
	ds_write_b128 v232, v[132:135] offset:64512
	global_load_dwordx4 v[128:131], v230, s[94:95] offset:768
	global_load_dwordx4 v[132:135], v231, s[94:95]
	s_waitcnt lgkmcnt(7)
	v_mfma_f32_32x32x16_bf16 v[112:127], v[234:237], v[184:187], v[112:127]
	ds_read_b64_tr_b16 v[242:243], v172 offset:64512
	ds_read_b64_tr_b16 v[244:245], v233 offset:29952
	ds_read_b64_tr_b16 v[246:247], v172 offset:64576
	ds_read_b64_tr_b16 v[248:249], v233 offset:30016
	v_mfma_f32_32x32x16_bf16 v[96:111], v[238:241], v[184:187], v[96:111]
	ds_read_b128 v[184:187], v165 offset:96
	s_waitcnt lgkmcnt(11)
	v_mfma_f32_32x32x16_bf16 v[80:95], v[234:237], v[188:191], v[80:95]
	v_mfma_f32_32x32x16_bf16 v[64:79], v[238:241], v[188:191], v[64:79]
	ds_read_b128 v[188:191], v165 offset:4704
	s_waitcnt lgkmcnt(9)
	v_mfma_f32_32x32x16_bf16 v[48:63], v[234:237], v[218:221], v[48:63]
	v_mfma_f32_32x32x16_bf16 v[32:47], v[238:241], v[218:221], v[32:47]
	ds_read_b128 v[218:221], v165 offset:9312
	s_waitcnt lgkmcnt(9)
	v_mfma_f32_32x32x16_bf16 v[16:31], v[234:237], v[222:225], v[16:31]
	v_mfma_f32_32x32x16_bf16 v[0:15], v[238:241], v[222:225], v[0:15]
	ds_read_b128 v[222:225], v165 offset:13920
	s_waitcnt lgkmcnt(3)
	v_mfma_f32_32x32x16_bf16 v[112:127], v[242:245], v[184:187], v[112:127]
	v_mfma_f32_32x32x16_bf16 v[96:111], v[246:249], v[184:187], v[96:111]
	s_waitcnt lgkmcnt(2)
	v_mfma_f32_32x32x16_bf16 v[80:95], v[242:245], v[188:191], v[80:95]
	v_mfma_f32_32x32x16_bf16 v[64:79], v[246:249], v[188:191], v[64:79]
	s_and_b32 s0, s11, 1
	s_mul_i32 s1, s0, 0x12000
	v_add3_u32 v172, s1, v180, v181
	v_add3_u32 v165, s1, v167, v179
	s_xor_b32 s0, s0, 1
	s_mul_i32 s0, s0, 0x12000
	v_add_u32_e32 v233, 0x9000, v172
	v_add_u32_e32 v217, s0, v166
	v_add_u32_e32 v232, s0, v183
	s_cmp_eq_u32 s11, 42
	s_waitcnt lgkmcnt(0)
	s_barrier
	s_cbranch_scc0 .LBB0_1487
; DI f32x16 mfma32(bf16x8 a, bf16x8 b, f32x16 c) { return __builtin_amdgcn_mfma_f32_32x32x16_bf16(a, b, c, 0, 0, 0); }
; DI s16x4 tr_read(const char* p) { bfx4 r = __builtin_amdgcn_ds_read_tr16_b64_v4bf16((LDS_AS bfx4*)p); return __builtin_bit_cast(s16x4, r); }
; DI bf16x8 cat8(s16x4 lo, s16x4 hi) { return __builtin_shufflevector(lo, hi, 0, 1, 2, 3, 4, 5, 6, 7); }
; template <int BM, class Epi>
; DI void gemm_tile(const bf16_t* __restrict__ A, int lda, const bf16_t* __restrict__ B, int ldb, int K, int row0, int col0, const Epi& epi, char* smem) {
;     ...
;     for (int kt = 0; kt < nk; ++kt) {
;         const char* cur = smem + (kt & 1) * GSTAGE;
;         char* nxt = smem + ((kt & 1) ^ 1) * GSTAGE;
;         const bool w1 = kt + 1 < nk, l2 = kt + 2 < nk;
;         const bf16_t* a2 = ag + (size_t)(kt + 2) * 64; const bf16_t* b2 = bg + (size_t)(kt + 2) * 64 * ldb;
; #pragma unroll
;         for (int s = 0; s < 4; ++s) {
;             bf16x8 xf[MI], wf[2];
; #pragma unroll
;             for (int mi = 0; mi < MI; ++mi) xf[mi] = *(const bf16x8*)(cur + xoff + mi * 32 * GA_S + s * 32);
; #pragma unroll
;             for (int ni = 0; ni < 2; ++ni) {
;                 const char* wp = cur + woff + s * 16 * GB_S + ni * 64;
;                 wf[ni] = cat8(tr_read(wp), tr_read(wp + 4 * GB_S));
;             }
; #pragma unroll
;             for (int mi = 0; mi < MI; ++mi)
; #pragma unroll
;                 for (int ni = 0; ni < 2; ++ni) acc[mi][ni] = mfma32(wf[ni], xf[mi], acc[mi][ni]);
;             if (w1) {
;                 if (s < NA_) *(u32x4*)(nxt + aw + 64 * s * GA_S) = ra[s];
;                 *(u32x4*)(nxt + bw + 16 * s * GB_S) = rb[s];
;             }
;             if (l2) {
;                 if (s < NA_) ra[s] = *(const u32x4*)(a2 + (size_t)(64 * s) * lda);
;                 rb[s] = *(const u32x4*)(b2 + (size_t)(16 * s) * ldb);
;             }
;         }
;         __syncthreads();
;     }
	v_mfma_f32_32x32x16_bf16 v[48:63], v[242:245], v[218:221], v[48:63]
	v_mfma_f32_32x32x16_bf16 v[32:47], v[246:249], v[218:221], v[32:47]
	v_mfma_f32_32x32x16_bf16 v[16:31], v[242:245], v[222:225], v[16:31]
	v_mfma_f32_32x32x16_bf16 v[0:15], v[246:249], v[222:225], v[0:15]
	s_add_i32 s0, 0, 0x12000
	v_add3_u32 v165, 0, v167, v179
	v_add3_u32 v164, v182, v164, s0
	v_add3_u32 v172, 0, v180, v181
	ds_read_b128 v[168:171], v165
	ds_read_b128 v[182:185], v165 offset:4608
	ds_read_b128 v[186:189], v165 offset:9216
	ds_read_b128 v[190:193], v165 offset:13824
	ds_read_b64_tr_b16 v[218:219], v172 offset:36864
	ds_read_b64_tr_b16 v[220:221], v172 offset:39168
	ds_read_b64_tr_b16 v[222:223], v172 offset:36928
	ds_read_b64_tr_b16 v[224:225], v172 offset:39232
	s_waitcnt lgkmcnt(2)
	v_mfma_f32_32x32x16_bf16 v[112:127], v[218:221], v[168:171], v[112:127]
	v_add_u32_e32 v166, s0, v166
	s_waitcnt vmcnt(7)
	ds_write_b128 v166, v[152:155]
	s_waitcnt vmcnt(6)
	ds_write_b128 v164, v[156:159] offset:36864
	v_add_u32_e32 v217, 0x9000, v172
	s_add_i32 s3, s3, s15
	s_cmp_gt_i32 s3, 63
	s_waitcnt lgkmcnt(2)
	v_mfma_f32_32x32x16_bf16 v[96:111], v[222:225], v[168:171], v[96:111]
	v_mfma_f32_32x32x16_bf16 v[48:63], v[218:221], v[186:189], v[48:63]
	v_mfma_f32_32x32x16_bf16 v[32:47], v[222:225], v[186:189], v[32:47]
	v_mfma_f32_32x32x16_bf16 v[80:95], v[218:221], v[182:185], v[80:95]
	v_mfma_f32_32x32x16_bf16 v[64:79], v[222:225], v[182:185], v[64:79]
	v_mfma_f32_32x32x16_bf16 v[16:31], v[218:221], v[190:193], v[16:31]
	v_mfma_f32_32x32x16_bf16 v[0:15], v[222:225], v[190:193], v[0:15]
	ds_read_b128 v[152:155], v165 offset:32
	ds_read_b128 v[156:159], v165 offset:4640
	ds_read_b128 v[168:171], v165 offset:9248
	ds_read_b128 v[182:185], v165 offset:13856
	ds_read_b64_tr_b16 v[186:187], v172 offset:46080
	ds_read_b64_tr_b16 v[188:189], v172 offset:48384
	ds_read_b64_tr_b16 v[190:191], v172 offset:46144
	ds_read_b64_tr_b16 v[192:193], v172 offset:48448
	s_waitcnt vmcnt(5)
	ds_write_b128 v166, v[144:147] offset:9216
	s_waitcnt vmcnt(4)
	ds_write_b128 v164, v[148:151] offset:46080
	s_waitcnt lgkmcnt(4)
	v_mfma_f32_32x32x16_bf16 v[112:127], v[186:189], v[152:155], v[112:127]
	s_waitcnt lgkmcnt(2)
	v_mfma_f32_32x32x16_bf16 v[96:111], v[190:193], v[152:155], v[96:111]
	v_mfma_f32_32x32x16_bf16 v[48:63], v[186:189], v[168:171], v[48:63]
	v_mfma_f32_32x32x16_bf16 v[32:47], v[190:193], v[168:171], v[32:47]
	v_mfma_f32_32x32x16_bf16 v[80:95], v[186:189], v[156:159], v[80:95]
	v_mfma_f32_32x32x16_bf16 v[64:79], v[190:193], v[156:159], v[64:79]
	v_mfma_f32_32x32x16_bf16 v[16:31], v[186:189], v[182:185], v[16:31]
	v_mfma_f32_32x32x16_bf16 v[0:15], v[190:193], v[182:185], v[0:15]
	ds_read_b128 v[144:147], v165 offset:64
	ds_read_b128 v[148:151], v165 offset:4672
	ds_read_b128 v[152:155], v165 offset:9280
	ds_read_b128 v[156:159], v165 offset:13888
	ds_read_b64_tr_b16 v[168:169], v172 offset:55296
	ds_read_b64_tr_b16 v[170:171], v172 offset:57600
	ds_read_b64_tr_b16 v[182:183], v172 offset:55360
	ds_read_b64_tr_b16 v[184:185], v172 offset:57664
	s_waitcnt vmcnt(3)
	ds_write_b128 v166, v[136:139] offset:18432
	s_waitcnt vmcnt(2)
	ds_write_b128 v164, v[140:143] offset:55296
	s_waitcnt lgkmcnt(4)
	v_mfma_f32_32x32x16_bf16 v[112:127], v[168:171], v[144:147], v[112:127]
	s_waitcnt lgkmcnt(2)
	v_mfma_f32_32x32x16_bf16 v[96:111], v[182:185], v[144:147], v[96:111]
	v_mfma_f32_32x32x16_bf16 v[48:63], v[168:171], v[152:155], v[48:63]
	v_mfma_f32_32x32x16_bf16 v[32:47], v[182:185], v[152:155], v[32:47]
	v_mfma_f32_32x32x16_bf16 v[80:95], v[168:171], v[148:151], v[80:95]
	v_mfma_f32_32x32x16_bf16 v[64:79], v[182:185], v[148:151], v[64:79]
	v_mfma_f32_32x32x16_bf16 v[16:31], v[168:171], v[156:159], v[16:31]
	v_mfma_f32_32x32x16_bf16 v[0:15], v[182:185], v[156:159], v[0:15]
	ds_read_b128 v[136:139], v165 offset:96
	ds_read_b128 v[140:143], v165 offset:4704
	ds_read_b128 v[144:147], v165 offset:9312
	ds_read_b128 v[148:151], v165 offset:13920
	ds_read_b64_tr_b16 v[152:153], v172 offset:64512
	ds_read_b64_tr_b16 v[154:155], v217 offset:29952
	ds_read_b64_tr_b16 v[156:157], v172 offset:64576
	ds_read_b64_tr_b16 v[158:159], v217 offset:30016
	s_waitcnt vmcnt(1)
	ds_write_b128 v166, v[128:131] offset:27648
	s_waitcnt vmcnt(0)
	ds_write_b128 v164, v[132:135] offset:64512
	s_waitcnt lgkmcnt(0)
	s_barrier
; DI unsigned pk2(float a, float b) { f32x2 v = {a, b}; bfx2 r = __builtin_convertvector(v, bfx2); return __builtin_bit_cast(unsigned, r); }
; DI f32x16 mfma32(bf16x8 a, bf16x8 b, f32x16 c) { return __builtin_amdgcn_mfma_f32_32x32x16_bf16(a, b, c, 0, 0, 0); }
; DI s16x4 tr_read(const char* p) { bfx4 r = __builtin_amdgcn_ds_read_tr16_b64_v4bf16((LDS_AS bfx4*)p); return __builtin_bit_cast(s16x4, r); }
; template <int BM, class Epi>
; DI void gemm_tile(const bf16_t* __restrict__ A, int lda, const bf16_t* __restrict__ B, int ldb, int K, int row0, int col0, const Epi& epi, char* smem) {
;     ...
;         for (int s = 0; s < 4; ++s) {
;             bf16x8 xf[MI], wf[2];
; #pragma unroll
;             for (int mi = 0; mi < MI; ++mi) xf[mi] = *(const bf16x8*)(cur + xoff + mi * 32 * GA_S + s * 32);
; #pragma unroll
;             for (int ni = 0; ni < 2; ++ni) {
;                 const char* wp = cur + woff + s * 16 * GB_S + ni * 64;
;                 wf[ni] = cat8(tr_read(wp), tr_read(wp + 4 * GB_S));
;             }
; #pragma unroll
;             for (int mi = 0; mi < MI; ++mi)
; #pragma unroll
;                 for (int ni = 0; ni < 2; ++ni) acc[mi][ni] = mfma32(wf[ni], xf[mi], acc[mi][ni]);
;             if (w1) {
;                 if (s < NA_) *(u32x4*)(nxt + aw + 64 * s * GA_S) = ra[s];
;                 *(u32x4*)(nxt + bw + 16 * s * GB_S) = rb[s];
;             }
;             if (l2) {
;                 if (s < NA_) ra[s] = *(const u32x4*)(a2 + (size_t)(64 * s) * lda);
;                 rb[s] = *(const u32x4*)(b2 + (size_t)(16 * s) * ldb);
;             }
;         }
;         __syncthreads();
;     DI void operator()(const f32x16& a0, const f32x16& a1, int row, int cbase, int hh) const {
;         const int s = row < RL ? (row >> 13) : 4;
;         const float* gp = gate + s * 9216;
;         bf16_t* yp = Y + (size_t)row * 1024;
; #pragma unroll
;         for (int ni = 0; ni < 2; ++ni)
; #pragma unroll
;             for (int q4 = 0; q4 < 4; ++q4) {
;                 const int c = cbase + ni * 32 + 8 * q4 + 4 * hh;
;                 const f32x4 g = *(const f32x4*)(gp + c);
;                 const f32x16& v = ni ? a1 : a0;
;                 u32x2 w; w.x = pk2(coef * g[0] * v[4 * q4], coef * g[1] * v[4 * q4 + 1]); w.y = pk2(coef * g[2] * v[4 * q4 + 2], coef * g[3] * v[4 * q4 + 3]);
;                 *(u32x2*)(yp + c) = w;
;             }
	v_mfma_f32_32x32x16_bf16 v[112:127], v[152:155], v[136:139], v[112:127]
	v_mfma_f32_32x32x16_bf16 v[96:111], v[156:159], v[136:139], v[96:111]
	v_mfma_f32_32x32x16_bf16 v[48:63], v[152:155], v[144:147], v[48:63]
	v_mfma_f32_32x32x16_bf16 v[32:47], v[156:159], v[144:147], v[32:47]
	v_mfma_f32_32x32x16_bf16 v[80:95], v[152:155], v[140:143], v[80:95]
	v_mfma_f32_32x32x16_bf16 v[64:79], v[156:159], v[140:143], v[64:79]
	v_mfma_f32_32x32x16_bf16 v[16:31], v[152:155], v[148:151], v[16:31]
	v_mfma_f32_32x32x16_bf16 v[0:15], v[156:159], v[148:151], v[0:15]
	v_add3_u32 v156, s0, v167, v179
	v_add3_u32 v157, s0, v180, v181
	ds_read_b128 v[128:131], v156 offset:4608
	ds_read_b128 v[132:135], v156 offset:9216
	ds_read_b128 v[136:139], v156 offset:13824
	ds_read_b64_tr_b16 v[140:141], v157 offset:36864
	ds_read_b64_tr_b16 v[142:143], v157 offset:39168
	ds_read_b64_tr_b16 v[144:145], v157 offset:36928
	ds_read_b64_tr_b16 v[146:147], v157 offset:39232
	ds_read_b128 v[148:151], v156
	ds_read_b128 v[152:155], v156 offset:32
	v_add_u32_e32 v158, 0x9000, v157
	v_readlane_b32 s0, v253, 5
	v_readlane_b32 s1, v253, 6
	s_waitcnt lgkmcnt(1)
	v_mfma_f32_32x32x16_bf16 v[112:127], v[140:143], v[148:151], v[112:127]
	v_mfma_f32_32x32x16_bf16 v[96:111], v[144:147], v[148:151], v[96:111]
	v_mfma_f32_32x32x16_bf16 v[48:63], v[140:143], v[132:135], v[48:63]
	v_mfma_f32_32x32x16_bf16 v[32:47], v[144:147], v[132:135], v[32:47]
	v_mfma_f32_32x32x16_bf16 v[80:95], v[140:143], v[128:131], v[80:95]
	v_mfma_f32_32x32x16_bf16 v[64:79], v[144:147], v[128:131], v[64:79]
	v_mfma_f32_32x32x16_bf16 v[16:31], v[140:143], v[136:139], v[16:31]
	v_mfma_f32_32x32x16_bf16 v[0:15], v[144:147], v[136:139], v[0:15]
	ds_read_b128 v[128:131], v156 offset:4640
	ds_read_b128 v[132:135], v156 offset:9248
	ds_read_b128 v[136:139], v156 offset:13856
	ds_read_b64_tr_b16 v[140:141], v157 offset:46080
	ds_read_b64_tr_b16 v[142:143], v157 offset:48384
	ds_read_b64_tr_b16 v[144:145], v157 offset:46144
	ds_read_b64_tr_b16 v[146:147], v157 offset:48448
	s_waitcnt lgkmcnt(2)
	v_mfma_f32_32x32x16_bf16 v[112:127], v[140:143], v[152:155], v[112:127]
	s_waitcnt lgkmcnt(0)
	v_mfma_f32_32x32x16_bf16 v[96:111], v[144:147], v[152:155], v[96:111]
	v_mfma_f32_32x32x16_bf16 v[48:63], v[140:143], v[132:135], v[48:63]
	v_mfma_f32_32x32x16_bf16 v[32:47], v[144:147], v[132:135], v[32:47]
	v_mfma_f32_32x32x16_bf16 v[80:95], v[140:143], v[128:131], v[80:95]
	v_mfma_f32_32x32x16_bf16 v[64:79], v[144:147], v[128:131], v[64:79]
	v_mfma_f32_32x32x16_bf16 v[16:31], v[140:143], v[136:139], v[16:31]
	v_mfma_f32_32x32x16_bf16 v[0:15], v[144:147], v[136:139], v[0:15]
	ds_read_b128 v[128:131], v156 offset:64
	ds_read_b128 v[132:135], v156 offset:4672
	ds_read_b128 v[136:139], v156 offset:9280
	ds_read_b128 v[140:143], v156 offset:13888
	ds_read_b64_tr_b16 v[144:145], v157 offset:55296
	ds_read_b64_tr_b16 v[146:147], v157 offset:57600
	ds_read_b64_tr_b16 v[148:149], v157 offset:55360
	ds_read_b64_tr_b16 v[150:151], v157 offset:57664
	s_waitcnt lgkmcnt(2)
	v_mfma_f32_32x32x16_bf16 v[112:127], v[144:147], v[128:131], v[112:127]
	s_waitcnt lgkmcnt(0)
	v_mfma_f32_32x32x16_bf16 v[96:111], v[148:151], v[128:131], v[96:111]
	v_mfma_f32_32x32x16_bf16 v[48:63], v[144:147], v[136:139], v[48:63]
	v_mfma_f32_32x32x16_bf16 v[32:47], v[148:151], v[136:139], v[32:47]
	v_mfma_f32_32x32x16_bf16 v[80:95], v[144:147], v[132:135], v[80:95]
	v_mfma_f32_32x32x16_bf16 v[64:79], v[148:151], v[132:135], v[64:79]
	v_mfma_f32_32x32x16_bf16 v[16:31], v[144:147], v[140:143], v[16:31]
	v_mfma_f32_32x32x16_bf16 v[0:15], v[148:151], v[140:143], v[0:15]
	ds_read_b128 v[128:131], v156 offset:96
	ds_read_b128 v[132:135], v156 offset:4704
	ds_read_b128 v[136:139], v156 offset:9312
	ds_read_b128 v[140:143], v156 offset:13920
	ds_read_b64_tr_b16 v[144:145], v157 offset:64512
	ds_read_b64_tr_b16 v[146:147], v158 offset:29952
	ds_read_b64_tr_b16 v[148:149], v157 offset:64576
	ds_read_b64_tr_b16 v[150:151], v158 offset:30016
	s_waitcnt lgkmcnt(0)
	s_barrier
	v_mfma_f32_32x32x16_bf16 v[112:127], v[144:147], v[128:131], v[112:127]
	v_mfma_f32_32x32x16_bf16 v[96:111], v[148:151], v[128:131], v[96:111]
	v_or_b32_e32 v128, s16, v176
	v_and_b32_e32 v129, 0xc0, v175
	v_add_u32_e32 v128, v128, v178
	v_lshlrev_b32_e32 v130, 2, v177
	v_mfma_f32_32x32x16_bf16 v[48:63], v[144:147], v[136:139], v[48:63]
	v_mfma_f32_32x32x16_bf16 v[32:47], v[148:151], v[136:139], v[32:47]
	v_or3_b32 v138, v130, v129, s10
	v_min_i32_e32 v129, 0x8000, v128
	v_ashrrev_i32_e32 v129, 13, v129
	v_mul_i32_i24_e32 v130, 0x2400, v129
	v_ashrrev_i32_e32 v131, 31, v130
	v_ashrrev_i32_e32 v129, 31, v128
	v_ashrrev_i32_e32 v139, 31, v138
	v_mfma_f32_32x32x16_bf16 v[80:95], v[144:147], v[132:135], v[80:95]
	v_mfma_f32_32x32x16_bf16 v[64:79], v[148:151], v[132:135], v[64:79]
	v_lshl_add_u64 v[132:133], v[130:131], 2, s[4:5]
	v_lshlrev_b64 v[130:131], 11, v[128:129]
	v_mfma_f32_32x32x16_bf16 v[16:31], v[144:147], v[140:143], v[16:31]
	v_mfma_f32_32x32x16_bf16 v[0:15], v[148:151], v[140:143], v[0:15]
	v_lshl_add_u64 v[140:141], s[0:1], 0, v[130:131]
	v_lshlrev_b64 v[130:131], 2, v[138:139]
	v_lshl_add_u64 v[132:133], v[132:133], 0, v[130:131]
	global_load_dwordx4 v[218:221], v[132:133], off
	global_load_dwordx4 v[222:225], v[132:133], off offset:32
	global_load_dwordx4 v[226:229], v[132:133], off offset:64
	global_load_dwordx4 v[230:233], v[132:133], off offset:96
	global_load_dwordx4 v[234:237], v[132:133], off offset:128
	global_load_dwordx4 v[238:241], v[132:133], off offset:160
	global_load_dwordx4 v[242:245], v[132:133], off offset:192
	global_load_dwordx4 v[246:249], v[132:133], off offset:224
	s_waitcnt vmcnt(0)
; DI unsigned pk2(float a, float b) { f32x2 v = {a, b}; bfx2 r = __builtin_convertvector(v, bfx2); return __builtin_bit_cast(unsigned, r); }
;     DI void operator()(const f32x16& a0, const f32x16& a1, int row, int cbase, int hh) const {
;         const int s = row < RL ? (row >> 13) : 4;
;         const float* gp = gate + s * 9216;
;         bf16_t* yp = Y + (size_t)row * 1024;
; #pragma unroll
;         for (int ni = 0; ni < 2; ++ni)
; #pragma unroll
;             for (int q4 = 0; q4 < 4; ++q4) {
;                 const int c = cbase + ni * 32 + 8 * q4 + 4 * hh;
;                 const f32x4 g = *(const f32x4*)(gp + c);
;                 const f32x16& v = ni ? a1 : a0;
;                 u32x2 w; w.x = pk2(coef * g[0] * v[4 * q4], coef * g[1] * v[4 * q4 + 1]); w.y = pk2(coef * g[2] * v[4 * q4 + 2], coef * g[3] * v[4 * q4 + 3]);
;                 *(u32x2*)(yp + c) = w;
;             }
	v_pk_mul_f32 v[134:135], v[218:219], 0.5 op_sel_hi:[1,0]
	s_nop 0
	v_pk_mul_f32 v[112:113], v[112:113], v[134:135]
	s_nop 0
	v_cvt_pk_bf16_f32 v134, v112, v113
	v_pk_mul_f32 v[112:113], v[220:221], 0.5 op_sel_hi:[1,0]
	s_nop 0
	v_pk_mul_f32 v[112:113], v[114:115], v[112:113]
	s_nop 0
	v_cvt_pk_bf16_f32 v135, v112, v113
	v_lshlrev_b64 v[112:113], 1, v[138:139]
	v_lshl_add_u64 v[138:139], v[140:141], 0, v[112:113]
	global_store_dwordx2 v[138:139], v[134:135], off
	v_pk_mul_f32 v[114:115], v[222:223], 0.5 op_sel_hi:[1,0]
	s_nop 0
	v_pk_mul_f32 v[114:115], v[116:117], v[114:115]
	v_pk_mul_f32 v[116:117], v[224:225], 0.5 op_sel_hi:[1,0]
	v_cvt_pk_bf16_f32 v114, v114, v115
	v_pk_mul_f32 v[116:117], v[118:119], v[116:117]
	s_nop 0
	v_cvt_pk_bf16_f32 v115, v116, v117
	global_store_dwordx2 v[138:139], v[114:115], off offset:16
	v_pk_mul_f32 v[114:115], v[226:227], 0.5 op_sel_hi:[1,0]
	v_pk_mul_f32 v[116:117], v[228:229], 0.5 op_sel_hi:[1,0]
	v_pk_mul_f32 v[114:115], v[120:121], v[114:115]
	v_pk_mul_f32 v[116:117], v[122:123], v[116:117]
	v_cvt_pk_bf16_f32 v114, v114, v115
	v_cvt_pk_bf16_f32 v115, v116, v117
	global_store_dwordx2 v[138:139], v[114:115], off offset:32
	v_pk_mul_f32 v[114:115], v[230:231], 0.5 op_sel_hi:[1,0]
	v_pk_mul_f32 v[116:117], v[232:233], 0.5 op_sel_hi:[1,0]
	v_pk_mul_f32 v[114:115], v[124:125], v[114:115]
	v_pk_mul_f32 v[116:117], v[126:127], v[116:117]
	v_cvt_pk_bf16_f32 v114, v114, v115
	v_cvt_pk_bf16_f32 v115, v116, v117
	global_store_dwordx2 v[138:139], v[114:115], off offset:48
	v_pk_mul_f32 v[114:115], v[234:235], 0.5 op_sel_hi:[1,0]
	s_nop 0
	v_pk_mul_f32 v[96:97], v[96:97], v[114:115]
	v_pk_mul_f32 v[114:115], v[236:237], 0.5 op_sel_hi:[1,0]
	v_cvt_pk_bf16_f32 v96, v96, v97
	v_pk_mul_f32 v[98:99], v[98:99], v[114:115]
	s_nop 0
	v_cvt_pk_bf16_f32 v97, v98, v99
	global_store_dwordx2 v[138:139], v[96:97], off offset:64
	v_pk_mul_f32 v[96:97], v[238:239], 0.5 op_sel_hi:[1,0]
	v_pk_mul_f32 v[98:99], v[240:241], 0.5 op_sel_hi:[1,0]
	v_pk_mul_f32 v[96:97], v[100:101], v[96:97]
	v_pk_mul_f32 v[98:99], v[102:103], v[98:99]
	v_cvt_pk_bf16_f32 v96, v96, v97
	v_cvt_pk_bf16_f32 v97, v98, v99
	global_store_dwordx2 v[138:139], v[96:97], off offset:80
	v_pk_mul_f32 v[96:97], v[242:243], 0.5 op_sel_hi:[1,0]
	v_pk_mul_f32 v[98:99], v[244:245], 0.5 op_sel_hi:[1,0]
	v_pk_mul_f32 v[96:97], v[104:105], v[96:97]
	v_pk_mul_f32 v[98:99], v[106:107], v[98:99]
	v_cvt_pk_bf16_f32 v96, v96, v97
	v_cvt_pk_bf16_f32 v97, v98, v99
	global_store_dwordx2 v[138:139], v[96:97], off offset:96
	v_pk_mul_f32 v[96:97], v[246:247], 0.5 op_sel_hi:[1,0]
	v_pk_mul_f32 v[98:99], v[248:249], 0.5 op_sel_hi:[1,0]
	v_pk_mul_f32 v[96:97], v[108:109], v[96:97]
	v_pk_mul_f32 v[98:99], v[110:111], v[98:99]
	v_cvt_pk_bf16_f32 v96, v96, v97
	v_cvt_pk_bf16_f32 v97, v98, v99
	global_store_dwordx2 v[138:139], v[96:97], off offset:112
	v_or_b32_e32 v96, 32, v128
	v_min_i32_e32 v97, 0x8000, v96
	v_ashrrev_i32_e32 v97, 13, v97
	v_mul_i32_i24_e32 v98, 0x2400, v97
	v_ashrrev_i32_e32 v99, 31, v98
	v_ashrrev_i32_e32 v97, 31, v96
	v_lshl_add_u64 v[98:99], v[98:99], 2, s[4:5]
	v_lshlrev_b64 v[96:97], 11, v[96:97]
	v_lshl_add_u64 v[102:103], s[0:1], 0, v[96:97]
	v_lshl_add_u64 v[96:97], v[98:99], 0, v[130:131]
	global_load_dwordx4 v[218:221], v[96:97], off
	global_load_dwordx4 v[222:225], v[96:97], off offset:32
	global_load_dwordx4 v[226:229], v[96:97], off offset:64
	global_load_dwordx4 v[230:233], v[96:97], off offset:96
	global_load_dwordx4 v[234:237], v[96:97], off offset:128
	global_load_dwordx4 v[238:241], v[96:97], off offset:160
	global_load_dwordx4 v[242:245], v[96:97], off offset:192
	global_load_dwordx4 v[246:249], v[96:97], off offset:224
	s_waitcnt vmcnt(0)
	v_pk_mul_f32 v[98:99], v[218:219], 0.5 op_sel_hi:[1,0]
	s_nop 0
	v_pk_mul_f32 v[80:81], v[80:81], v[98:99]
	v_pk_mul_f32 v[98:99], v[220:221], 0.5 op_sel_hi:[1,0]
	v_cvt_pk_bf16_f32 v80, v80, v81
	v_pk_mul_f32 v[82:83], v[82:83], v[98:99]
	v_lshl_add_u64 v[98:99], v[102:103], 0, v[112:113]
	v_cvt_pk_bf16_f32 v81, v82, v83
	global_store_dwordx2 v[98:99], v[80:81], off
	v_pk_mul_f32 v[80:81], v[222:223], 0.5 op_sel_hi:[1,0]
	v_pk_mul_f32 v[82:83], v[224:225], 0.5 op_sel_hi:[1,0]
	v_pk_mul_f32 v[80:81], v[84:85], v[80:81]
	v_pk_mul_f32 v[82:83], v[86:87], v[82:83]
	v_cvt_pk_bf16_f32 v80, v80, v81
	v_cvt_pk_bf16_f32 v81, v82, v83
	global_store_dwordx2 v[98:99], v[80:81], off offset:16
	v_pk_mul_f32 v[80:81], v[226:227], 0.5 op_sel_hi:[1,0]
	v_pk_mul_f32 v[82:83], v[228:229], 0.5 op_sel_hi:[1,0]
	v_pk_mul_f32 v[80:81], v[88:89], v[80:81]
	v_pk_mul_f32 v[82:83], v[90:91], v[82:83]
	v_cvt_pk_bf16_f32 v80, v80, v81
	v_cvt_pk_bf16_f32 v81, v82, v83
	global_store_dwordx2 v[98:99], v[80:81], off offset:32
	v_pk_mul_f32 v[80:81], v[230:231], 0.5 op_sel_hi:[1,0]
	v_pk_mul_f32 v[82:83], v[232:233], 0.5 op_sel_hi:[1,0]
	v_pk_mul_f32 v[80:81], v[92:93], v[80:81]
	v_pk_mul_f32 v[82:83], v[94:95], v[82:83]
	v_cvt_pk_bf16_f32 v80, v80, v81
	v_cvt_pk_bf16_f32 v81, v82, v83
	global_store_dwordx2 v[98:99], v[80:81], off offset:48
	v_pk_mul_f32 v[80:81], v[234:235], 0.5 op_sel_hi:[1,0]
	s_nop 0
	v_pk_mul_f32 v[64:65], v[64:65], v[80:81]
	v_pk_mul_f32 v[80:81], v[236:237], 0.5 op_sel_hi:[1,0]
	v_cvt_pk_bf16_f32 v64, v64, v65
	v_pk_mul_f32 v[66:67], v[66:67], v[80:81]
	s_nop 0
	v_cvt_pk_bf16_f32 v65, v66, v67
	global_store_dwordx2 v[98:99], v[64:65], off offset:64
	v_pk_mul_f32 v[64:65], v[238:239], 0.5 op_sel_hi:[1,0]
	v_pk_mul_f32 v[66:67], v[240:241], 0.5 op_sel_hi:[1,0]
	v_pk_mul_f32 v[64:65], v[68:69], v[64:65]
	v_pk_mul_f32 v[66:67], v[70:71], v[66:67]
	v_cvt_pk_bf16_f32 v64, v64, v65
	v_cvt_pk_bf16_f32 v65, v66, v67
; DI unsigned pk2(float a, float b) { f32x2 v = {a, b}; bfx2 r = __builtin_convertvector(v, bfx2); return __builtin_bit_cast(unsigned, r); }
;     DI void operator()(const f32x16& a0, const f32x16& a1, int row, int cbase, int hh) const {
;         const int s = row < RL ? (row >> 13) : 4;
;         const float* gp = gate + s * 9216;
;         bf16_t* yp = Y + (size_t)row * 1024;
; #pragma unroll
;         for (int ni = 0; ni < 2; ++ni)
; #pragma unroll
;             for (int q4 = 0; q4 < 4; ++q4) {
;                 const int c = cbase + ni * 32 + 8 * q4 + 4 * hh;
;                 const f32x4 g = *(const f32x4*)(gp + c);
;                 const f32x16& v = ni ? a1 : a0;
;                 u32x2 w; w.x = pk2(coef * g[0] * v[4 * q4], coef * g[1] * v[4 * q4 + 1]); w.y = pk2(coef * g[2] * v[4 * q4 + 2], coef * g[3] * v[4 * q4 + 3]);
;                 *(u32x2*)(yp + c) = w;
;             }
	global_store_dwordx2 v[98:99], v[64:65], off offset:80
	v_pk_mul_f32 v[64:65], v[242:243], 0.5 op_sel_hi:[1,0]
	v_pk_mul_f32 v[66:67], v[244:245], 0.5 op_sel_hi:[1,0]
	v_pk_mul_f32 v[64:65], v[72:73], v[64:65]
	v_pk_mul_f32 v[66:67], v[74:75], v[66:67]
	v_cvt_pk_bf16_f32 v64, v64, v65
	v_cvt_pk_bf16_f32 v65, v66, v67
	global_store_dwordx2 v[98:99], v[64:65], off offset:96
	v_pk_mul_f32 v[64:65], v[246:247], 0.5 op_sel_hi:[1,0]
	v_pk_mul_f32 v[66:67], v[248:249], 0.5 op_sel_hi:[1,0]
	v_pk_mul_f32 v[64:65], v[76:77], v[64:65]
	v_pk_mul_f32 v[66:67], v[78:79], v[66:67]
	v_cvt_pk_bf16_f32 v64, v64, v65
	v_cvt_pk_bf16_f32 v65, v66, v67
	global_store_dwordx2 v[98:99], v[64:65], off offset:112
	v_or_b32_e32 v64, 64, v128
	v_min_i32_e32 v65, 0x8000, v64
	v_ashrrev_i32_e32 v65, 13, v65
	v_mul_i32_i24_e32 v66, 0x2400, v65
	v_ashrrev_i32_e32 v67, 31, v66
	v_ashrrev_i32_e32 v65, 31, v64
	v_lshl_add_u64 v[66:67], v[66:67], 2, s[4:5]
	v_lshlrev_b64 v[64:65], 11, v[64:65]
	v_lshl_add_u64 v[70:71], s[0:1], 0, v[64:65]
	v_lshl_add_u64 v[64:65], v[66:67], 0, v[130:131]
	global_load_dwordx4 v[218:221], v[64:65], off
	global_load_dwordx4 v[222:225], v[64:65], off offset:32
	global_load_dwordx4 v[226:229], v[64:65], off offset:64
	global_load_dwordx4 v[230:233], v[64:65], off offset:96
	global_load_dwordx4 v[234:237], v[64:65], off offset:128
	global_load_dwordx4 v[238:241], v[64:65], off offset:160
	global_load_dwordx4 v[242:245], v[64:65], off offset:192
	global_load_dwordx4 v[246:249], v[64:65], off offset:224
	s_waitcnt vmcnt(0)
	v_pk_mul_f32 v[66:67], v[218:219], 0.5 op_sel_hi:[1,0]
	s_nop 0
	v_pk_mul_f32 v[48:49], v[48:49], v[66:67]
	v_pk_mul_f32 v[66:67], v[220:221], 0.5 op_sel_hi:[1,0]
	v_cvt_pk_bf16_f32 v48, v48, v49
	v_pk_mul_f32 v[50:51], v[50:51], v[66:67]
	v_lshl_add_u64 v[66:67], v[70:71], 0, v[112:113]
	v_cvt_pk_bf16_f32 v49, v50, v51
	global_store_dwordx2 v[66:67], v[48:49], off
	v_pk_mul_f32 v[48:49], v[222:223], 0.5 op_sel_hi:[1,0]
	v_pk_mul_f32 v[50:51], v[224:225], 0.5 op_sel_hi:[1,0]
	v_pk_mul_f32 v[48:49], v[52:53], v[48:49]
	v_pk_mul_f32 v[50:51], v[54:55], v[50:51]
	v_cvt_pk_bf16_f32 v48, v48, v49
	v_cvt_pk_bf16_f32 v49, v50, v51
	global_store_dwordx2 v[66:67], v[48:49], off offset:16
	v_pk_mul_f32 v[48:49], v[226:227], 0.5 op_sel_hi:[1,0]
	v_pk_mul_f32 v[50:51], v[228:229], 0.5 op_sel_hi:[1,0]
	v_pk_mul_f32 v[48:49], v[56:57], v[48:49]
	v_pk_mul_f32 v[50:51], v[58:59], v[50:51]
	v_cvt_pk_bf16_f32 v48, v48, v49
	v_cvt_pk_bf16_f32 v49, v50, v51
	global_store_dwordx2 v[66:67], v[48:49], off offset:32
	v_pk_mul_f32 v[48:49], v[230:231], 0.5 op_sel_hi:[1,0]
	v_pk_mul_f32 v[50:51], v[232:233], 0.5 op_sel_hi:[1,0]
	v_pk_mul_f32 v[48:49], v[60:61], v[48:49]
	v_pk_mul_f32 v[50:51], v[62:63], v[50:51]
	v_cvt_pk_bf16_f32 v48, v48, v49
	v_cvt_pk_bf16_f32 v49, v50, v51
	global_store_dwordx2 v[66:67], v[48:49], off offset:48
	v_pk_mul_f32 v[48:49], v[234:235], 0.5 op_sel_hi:[1,0]
	s_nop 0
	v_pk_mul_f32 v[32:33], v[32:33], v[48:49]
	v_pk_mul_f32 v[48:49], v[236:237], 0.5 op_sel_hi:[1,0]
	v_cvt_pk_bf16_f32 v32, v32, v33
	v_pk_mul_f32 v[34:35], v[34:35], v[48:49]
	s_nop 0
	v_cvt_pk_bf16_f32 v33, v34, v35
	global_store_dwordx2 v[66:67], v[32:33], off offset:64
	v_pk_mul_f32 v[32:33], v[238:239], 0.5 op_sel_hi:[1,0]
	v_pk_mul_f32 v[34:35], v[240:241], 0.5 op_sel_hi:[1,0]
	v_pk_mul_f32 v[32:33], v[36:37], v[32:33]
	v_pk_mul_f32 v[34:35], v[38:39], v[34:35]
	v_cvt_pk_bf16_f32 v32, v32, v33
	v_cvt_pk_bf16_f32 v33, v34, v35
	global_store_dwordx2 v[66:67], v[32:33], off offset:80
	v_pk_mul_f32 v[32:33], v[242:243], 0.5 op_sel_hi:[1,0]
	v_pk_mul_f32 v[34:35], v[244:245], 0.5 op_sel_hi:[1,0]
	v_pk_mul_f32 v[32:33], v[40:41], v[32:33]
	v_pk_mul_f32 v[34:35], v[42:43], v[34:35]
	v_cvt_pk_bf16_f32 v32, v32, v33
	v_cvt_pk_bf16_f32 v33, v34, v35
	global_store_dwordx2 v[66:67], v[32:33], off offset:96
	v_pk_mul_f32 v[32:33], v[246:247], 0.5 op_sel_hi:[1,0]
	v_pk_mul_f32 v[34:35], v[248:249], 0.5 op_sel_hi:[1,0]
	v_pk_mul_f32 v[32:33], v[44:45], v[32:33]
	v_pk_mul_f32 v[34:35], v[46:47], v[34:35]
	v_cvt_pk_bf16_f32 v32, v32, v33
	v_cvt_pk_bf16_f32 v33, v34, v35
	global_store_dwordx2 v[66:67], v[32:33], off offset:112
	v_or_b32_e32 v32, 0x60, v128
	v_min_i32_e32 v33, 0x8000, v32
	v_ashrrev_i32_e32 v33, 13, v33
	v_mul_i32_i24_e32 v34, 0x2400, v33
	v_ashrrev_i32_e32 v35, 31, v34
	v_ashrrev_i32_e32 v33, 31, v32
	v_lshl_add_u64 v[34:35], v[34:35], 2, s[4:5]
	v_lshlrev_b64 v[32:33], 11, v[32:33]
	v_lshl_add_u64 v[38:39], s[0:1], 0, v[32:33]
	v_lshl_add_u64 v[32:33], v[34:35], 0, v[130:131]
	global_load_dwordx4 v[218:221], v[32:33], off
	global_load_dwordx4 v[222:225], v[32:33], off offset:32
	global_load_dwordx4 v[226:229], v[32:33], off offset:64
	global_load_dwordx4 v[230:233], v[32:33], off offset:96
	global_load_dwordx4 v[234:237], v[32:33], off offset:128
	global_load_dwordx4 v[238:241], v[32:33], off offset:160
	global_load_dwordx4 v[242:245], v[32:33], off offset:192
	global_load_dwordx4 v[246:249], v[32:33], off offset:224
	s_waitcnt vmcnt(0)
; DI unsigned pk2(float a, float b) { f32x2 v = {a, b}; bfx2 r = __builtin_convertvector(v, bfx2); return __builtin_bit_cast(unsigned, r); }
;     DI void operator()(const f32x16& a0, const f32x16& a1, int row, int cbase, int hh) const {
;         const int s = row < RL ? (row >> 13) : 4;
;         const float* gp = gate + s * 9216;
;         bf16_t* yp = Y + (size_t)row * 1024;
; #pragma unroll
;         for (int ni = 0; ni < 2; ++ni)
; #pragma unroll
;             for (int q4 = 0; q4 < 4; ++q4) {
;                 const int c = cbase + ni * 32 + 8 * q4 + 4 * hh;
;                 const f32x4 g = *(const f32x4*)(gp + c);
;                 const f32x16& v = ni ? a1 : a0;
;                 u32x2 w; w.x = pk2(coef * g[0] * v[4 * q4], coef * g[1] * v[4 * q4 + 1]); w.y = pk2(coef * g[2] * v[4 * q4 + 2], coef * g[3] * v[4 * q4 + 3]);
;                 *(u32x2*)(yp + c) = w;
;             }
	v_pk_mul_f32 v[34:35], v[218:219], 0.5 op_sel_hi:[1,0]
	s_nop 0
	v_pk_mul_f32 v[16:17], v[16:17], v[34:35]
	v_pk_mul_f32 v[34:35], v[220:221], 0.5 op_sel_hi:[1,0]
	v_cvt_pk_bf16_f32 v16, v16, v17
	v_pk_mul_f32 v[18:19], v[18:19], v[34:35]
	v_lshl_add_u64 v[34:35], v[38:39], 0, v[112:113]
	v_cvt_pk_bf16_f32 v17, v18, v19
	global_store_dwordx2 v[34:35], v[16:17], off
	v_pk_mul_f32 v[16:17], v[222:223], 0.5 op_sel_hi:[1,0]
	v_pk_mul_f32 v[18:19], v[224:225], 0.5 op_sel_hi:[1,0]
	v_pk_mul_f32 v[16:17], v[20:21], v[16:17]
	v_pk_mul_f32 v[18:19], v[22:23], v[18:19]
	v_cvt_pk_bf16_f32 v16, v16, v17
	v_cvt_pk_bf16_f32 v17, v18, v19
	global_store_dwordx2 v[34:35], v[16:17], off offset:16
	v_pk_mul_f32 v[16:17], v[226:227], 0.5 op_sel_hi:[1,0]
	v_pk_mul_f32 v[18:19], v[228:229], 0.5 op_sel_hi:[1,0]
	v_pk_mul_f32 v[16:17], v[24:25], v[16:17]
	v_pk_mul_f32 v[18:19], v[26:27], v[18:19]
	v_cvt_pk_bf16_f32 v16, v16, v17
	v_cvt_pk_bf16_f32 v17, v18, v19
	global_store_dwordx2 v[34:35], v[16:17], off offset:32
	v_pk_mul_f32 v[16:17], v[230:231], 0.5 op_sel_hi:[1,0]
	v_pk_mul_f32 v[18:19], v[232:233], 0.5 op_sel_hi:[1,0]
	v_pk_mul_f32 v[16:17], v[28:29], v[16:17]
	v_pk_mul_f32 v[18:19], v[30:31], v[18:19]
	v_cvt_pk_bf16_f32 v16, v16, v17
	v_cvt_pk_bf16_f32 v17, v18, v19
	global_store_dwordx2 v[34:35], v[16:17], off offset:48
	v_pk_mul_f32 v[16:17], v[234:235], 0.5 op_sel_hi:[1,0]
	s_nop 0
	v_pk_mul_f32 v[0:1], v[0:1], v[16:17]
	v_pk_mul_f32 v[16:17], v[236:237], 0.5 op_sel_hi:[1,0]
	v_cvt_pk_bf16_f32 v0, v0, v1
	v_pk_mul_f32 v[2:3], v[2:3], v[16:17]
	s_nop 0
	v_cvt_pk_bf16_f32 v1, v2, v3
	global_store_dwordx2 v[34:35], v[0:1], off offset:64
	v_pk_mul_f32 v[0:1], v[238:239], 0.5 op_sel_hi:[1,0]
	v_pk_mul_f32 v[2:3], v[240:241], 0.5 op_sel_hi:[1,0]
	v_pk_mul_f32 v[0:1], v[4:5], v[0:1]
	v_pk_mul_f32 v[2:3], v[6:7], v[2:3]
	v_cvt_pk_bf16_f32 v0, v0, v1
	v_cvt_pk_bf16_f32 v1, v2, v3
	global_store_dwordx2 v[34:35], v[0:1], off offset:80
	v_pk_mul_f32 v[0:1], v[242:243], 0.5 op_sel_hi:[1,0]
	v_pk_mul_f32 v[2:3], v[244:245], 0.5 op_sel_hi:[1,0]
	v_pk_mul_f32 v[0:1], v[8:9], v[0:1]
	v_pk_mul_f32 v[2:3], v[10:11], v[2:3]
	v_cvt_pk_bf16_f32 v0, v0, v1
	v_cvt_pk_bf16_f32 v1, v2, v3
	global_store_dwordx2 v[34:35], v[0:1], off offset:96
	v_pk_mul_f32 v[0:1], v[246:247], 0.5 op_sel_hi:[1,0]
	v_pk_mul_f32 v[2:3], v[248:249], 0.5 op_sel_hi:[1,0]
	v_pk_mul_f32 v[0:1], v[12:13], v[0:1]
	v_pk_mul_f32 v[2:3], v[14:15], v[2:3]
	v_cvt_pk_bf16_f32 v0, v0, v1
	v_cvt_pk_bf16_f32 v1, v2, v3
	global_store_dwordx2 v[34:35], v[0:1], off offset:112
	s_cbranch_scc0 .LBB0_1482

; DI f32x16 mfma32(bf16x8 a, bf16x8 b, f32x16 c) { return __builtin_amdgcn_mfma_f32_32x32x16_bf16(a, b, c, 0, 0, 0); }
; DI s16x4 tr_read(const char* p) { bfx4 r = __builtin_amdgcn_ds_read_tr16_b64_v4bf16((LDS_AS bfx4*)p); return __builtin_bit_cast(s16x4, r); }
; DI bf16x8 cat8(s16x4 lo, s16x4 hi) { return __builtin_shufflevector(lo, hi, 0, 1, 2, 3, 4, 5, 6, 7); }
; template <int BM, class Epi>
; DI void gemm_tile(const bf16_t* __restrict__ A, int lda, const bf16_t* __restrict__ B, int ldb, int K, int row0, int col0, const Epi& epi, char* smem) {
;     ...
;     for (int kt = 0; kt < nk; ++kt) {
;         const char* cur = smem + (kt & 1) * GSTAGE;
;         char* nxt = smem + ((kt & 1) ^ 1) * GSTAGE;
;         const bool w1 = kt + 1 < nk, l2 = kt + 2 < nk;
;         const bf16_t* a2 = ag + (size_t)(kt + 2) * 64; const bf16_t* b2 = bg + (size_t)(kt + 2) * 64 * ldb;
; #pragma unroll
;         for (int s = 0; s < 4; ++s) {
;             bf16x8 xf[MI], wf[2];
; #pragma unroll
;             for (int mi = 0; mi < MI; ++mi) xf[mi] = *(const bf16x8*)(cur + xoff + mi * 32 * GA_S + s * 32);
; #pragma unroll
;             for (int ni = 0; ni < 2; ++ni) {
;                 const char* wp = cur + woff + s * 16 * GB_S + ni * 64;
;                 wf[ni] = cat8(tr_read(wp), tr_read(wp + 4 * GB_S));
;             }
; #pragma unroll
;             for (int mi = 0; mi < MI; ++mi)
; #pragma unroll
;                 for (int ni = 0; ni < 2; ++ni) acc[mi][ni] = mfma32(wf[ni], xf[mi], acc[mi][ni]);
;             if (w1) {
;                 if (s < NA_) *(u32x4*)(nxt + aw + 64 * s * GA_S) = ra[s];
;                 *(u32x4*)(nxt + bw + 16 * s * GB_S) = rb[s];
;             }
;             if (l2) {
;                 if (s < NA_) ra[s] = *(const u32x4*)(a2 + (size_t)(64 * s) * lda);
;                 rb[s] = *(const u32x4*)(b2 + (size_t)(16 * s) * ldb);
;             }
;         }
;         __syncthreads();
;     }
.LBB0_1492:
	s_and_b32 s2, s1, 1
	s_mul_i32 s3, s2, 0x12000
	s_add_i32 s3, s3, 0
	v_add3_u32 v107, s3, v103, v104
	s_xor_b32 s2, s2, 1
	v_add3_u32 v91, s3, v93, v102
	ds_read_b64_tr_b16 v[108:109], v107 offset:18432
	ds_read_b64_tr_b16 v[110:111], v107 offset:20736
	ds_read_b128 v[112:115], v91
	ds_read_b128 v[116:119], v91 offset:4608
	ds_read_b64_tr_b16 v[122:123], v107 offset:20800
	ds_read_b64_tr_b16 v[120:121], v107 offset:18496
	s_mul_i32 s2, s2, 0x12000
	s_add_i32 s2, s2, 0
	v_add_u32_e32 v124, s2, v92
	v_add_u32_e32 v126, s2, v106
	s_waitcnt vmcnt(5)
	ds_write_b128 v124, v[80:83]
	s_waitcnt vmcnt(3)
	ds_write_b128 v126, v[84:87] offset:18432
	ds_read_b64_tr_b16 v[80:81], v107 offset:27648
	s_waitcnt lgkmcnt(6)
	v_mfma_f32_32x32x16_bf16 v[48:63], v[108:111], v[112:115], v[48:63]
	s_add_i32 s1, s1, 1
	s_cmp_eq_u32 s1, 42
	s_waitcnt lgkmcnt(3)
	v_mfma_f32_32x32x16_bf16 v[32:47], v[120:123], v[112:115], v[32:47]
	v_mfma_f32_32x32x16_bf16 v[16:31], v[108:111], v[116:119], v[16:31]
	ds_read_b64_tr_b16 v[82:83], v107 offset:29952
	ds_read_b128 v[84:87], v91 offset:32
	ds_read_b128 v[108:111], v91 offset:4640
	ds_read_b64_tr_b16 v[114:115], v107 offset:30016
	ds_read_b64_tr_b16 v[112:113], v107 offset:27712
	ds_write_b128 v124, v[72:75] offset:9216
	s_waitcnt vmcnt(2)
	ds_write_b128 v126, v[76:79] offset:27648
	ds_read_b64_tr_b16 v[72:73], v107 offset:36864
	v_mfma_f32_32x32x16_bf16 v[0:15], v[120:123], v[116:119], v[0:15]
	v_lshl_add_u64 v[120:121], s[94:95], 0, v[96:97]
	v_lshl_add_u64 v[96:97], v[96:97], 0, s[20:21]
	s_waitcnt lgkmcnt(6)
	v_mfma_f32_32x32x16_bf16 v[48:63], v[80:83], v[84:87], v[48:63]
	s_waitcnt lgkmcnt(3)
	v_mfma_f32_32x32x16_bf16 v[32:47], v[112:115], v[84:87], v[32:47]
	v_mfma_f32_32x32x16_bf16 v[16:31], v[80:83], v[108:111], v[16:31]
	ds_read_b64_tr_b16 v[74:75], v107 offset:39168
	ds_read_b128 v[76:79], v91 offset:64
	ds_read_b128 v[80:83], v91 offset:4672
	ds_read_b64_tr_b16 v[86:87], v107 offset:39232
	ds_read_b64_tr_b16 v[84:85], v107 offset:36928
	s_waitcnt vmcnt(1)
	ds_write_b128 v126, v[68:71] offset:36864
	v_mfma_f32_32x32x16_bf16 v[0:15], v[112:115], v[108:111], v[0:15]
	v_lshl_add_u64 v[108:109], s[94:95], 0, v[94:95]
	v_lshl_add_u64 v[94:95], v[94:95], 0, s[18:19]
	s_waitcnt lgkmcnt(4)
	v_mfma_f32_32x32x16_bf16 v[48:63], v[72:75], v[76:79], v[48:63]
	s_waitcnt lgkmcnt(1)
	v_mfma_f32_32x32x16_bf16 v[32:47], v[84:87], v[76:79], v[32:47]
	v_add_co_u32_e32 v76, vcc, s10, v108
	s_nop 1
	v_addc_co_u32_e32 v77, vcc, 0, v109, vcc
	v_add_co_u32_e32 v78, vcc, s11, v120
	v_mfma_f32_32x32x16_bf16 v[16:31], v[72:75], v[80:83], v[16:31]
	s_nop 0
	v_addc_co_u32_e32 v79, vcc, 0, v121, vcc
	v_add_co_u32_e32 v72, vcc, s14, v108
	s_nop 1
	v_addc_co_u32_e32 v73, vcc, 0, v109, vcc
	ds_read_b64_tr_b16 v[108:109], v107 offset:46080
	ds_read_b64_tr_b16 v[110:111], v107 offset:48384
	ds_read_b128 v[68:71], v91 offset:96
	ds_read_b128 v[112:115], v91 offset:4704
	ds_read_b64_tr_b16 v[118:119], v107 offset:48448
	ds_read_b64_tr_b16 v[116:117], v107 offset:46144
	v_add_co_u32_e32 v122, vcc, s15, v120
	v_mfma_f32_32x32x16_bf16 v[0:15], v[84:87], v[80:83], v[0:15]
	s_nop 0
	v_addc_co_u32_e32 v123, vcc, 0, v121, vcc
	v_add_co_u32_e32 v124, vcc, s16, v120
	s_nop 1
	v_addc_co_u32_e32 v125, vcc, 0, v121, vcc
	s_waitcnt lgkmcnt(3)
	v_mfma_f32_32x32x16_bf16 v[48:63], v[108:111], v[68:71], v[48:63]
	v_add_co_u32_e32 v120, vcc, s17, v120
	s_nop 1
	v_addc_co_u32_e32 v121, vcc, 0, v121, vcc
	s_waitcnt lgkmcnt(0)
	v_mfma_f32_32x32x16_bf16 v[32:47], v[116:119], v[68:71], v[32:47]
	global_load_dwordx4 v[80:83], v[76:77], off offset:768
	global_load_dwordx4 v[84:87], v[78:79], off
	s_nop 0
	global_load_dwordx4 v[72:75], v[72:73], off offset:768
	s_nop 0
	global_load_dwordx4 v[76:79], v[122:123], off
	global_load_dwordx4 v[68:71], v[124:125], off
	s_waitcnt vmcnt(5)
	ds_write_b128 v126, v[64:67] offset:46080
	global_load_dwordx4 v[64:67], v[120:121], off
	s_waitcnt lgkmcnt(0)
	s_barrier
	v_mfma_f32_32x32x16_bf16 v[16:31], v[108:111], v[112:115], v[16:31]
	v_mfma_f32_32x32x16_bf16 v[0:15], v[116:119], v[112:115], v[0:15]
	s_cbranch_scc0 .LBB0_1492
	s_add_i32 s1, 0, 0x12000
	v_add3_u32 v91, 0, v93, v102
	v_add3_u32 v90, v105, v90, s1
	v_add3_u32 v105, 0, v103, v104
	ds_read_b128 v[94:97], v91
	ds_read_b128 v[106:109], v91 offset:4608
	ds_read_b64_tr_b16 v[110:111], v105 offset:18432
	ds_read_b64_tr_b16 v[112:113], v105 offset:20736
	ds_read_b64_tr_b16 v[114:115], v105 offset:18496
	ds_read_b64_tr_b16 v[116:117], v105 offset:20800
	s_waitcnt lgkmcnt(2)
	v_mfma_f32_32x32x16_bf16 v[48:63], v[110:113], v[94:97], v[48:63]
	v_add_u32_e32 v92, s1, v92
	s_waitcnt vmcnt(5)
	ds_write_b128 v92, v[80:83]
	s_waitcnt vmcnt(4)
	ds_write_b128 v90, v[84:87] offset:18432
	s_add_i32 s12, s12, s13
	s_cmp_ge_i32 s12, s8
	s_waitcnt lgkmcnt(2)
	v_mfma_f32_32x32x16_bf16 v[32:47], v[114:117], v[94:97], v[32:47]
	v_mfma_f32_32x32x16_bf16 v[16:31], v[110:113], v[106:109], v[16:31]
	v_mfma_f32_32x32x16_bf16 v[0:15], v[114:117], v[106:109], v[0:15]
	ds_read_b128 v[80:83], v91 offset:32
	ds_read_b128 v[84:87], v91 offset:4640
	ds_read_b64_tr_b16 v[94:95], v105 offset:27648
	ds_read_b64_tr_b16 v[96:97], v105 offset:29952
	ds_read_b64_tr_b16 v[106:107], v105 offset:27712
	ds_read_b64_tr_b16 v[108:109], v105 offset:30016
	s_waitcnt vmcnt(3)
	ds_write_b128 v92, v[72:75] offset:9216
	s_waitcnt vmcnt(2)
	ds_write_b128 v90, v[76:79] offset:27648
	s_waitcnt lgkmcnt(4)
	v_mfma_f32_32x32x16_bf16 v[48:63], v[94:97], v[80:83], v[48:63]
	s_waitcnt lgkmcnt(2)
	v_mfma_f32_32x32x16_bf16 v[32:47], v[106:109], v[80:83], v[32:47]
	v_mfma_f32_32x32x16_bf16 v[16:31], v[94:97], v[84:87], v[16:31]
	v_mfma_f32_32x32x16_bf16 v[0:15], v[106:109], v[84:87], v[0:15]
	ds_read_b128 v[72:75], v91 offset:64
	ds_read_b128 v[76:79], v91 offset:4672
	ds_read_b64_tr_b16 v[80:81], v105 offset:36864
	ds_read_b64_tr_b16 v[82:83], v105 offset:39168
	ds_read_b64_tr_b16 v[84:85], v105 offset:36928
	ds_read_b64_tr_b16 v[86:87], v105 offset:39232
	s_waitcnt vmcnt(1)
	ds_write_b128 v90, v[68:71] offset:36864
	s_waitcnt lgkmcnt(3)
	v_mfma_f32_32x32x16_bf16 v[48:63], v[80:83], v[72:75], v[48:63]
	s_waitcnt lgkmcnt(1)
	v_mfma_f32_32x32x16_bf16 v[32:47], v[84:87], v[72:75], v[32:47]
	v_mfma_f32_32x32x16_bf16 v[16:31], v[80:83], v[76:79], v[16:31]
	v_mfma_f32_32x32x16_bf16 v[0:15], v[84:87], v[76:79], v[0:15]
	ds_read_b128 v[68:71], v91 offset:96
	ds_read_b128 v[72:75], v91 offset:4704
	ds_read_b64_tr_b16 v[76:77], v105 offset:46080
	ds_read_b64_tr_b16 v[78:79], v105 offset:48384
	ds_read_b64_tr_b16 v[80:81], v105 offset:46144
	ds_read_b64_tr_b16 v[82:83], v105 offset:48448
	v_add3_u32 v84, s1, v93, v102
	s_waitcnt vmcnt(0)
	ds_write_b128 v90, v[64:67] offset:46080
	s_waitcnt lgkmcnt(0)
	s_barrier
; DI unsigned pk2(float a, float b) { f32x2 v = {a, b}; bfx2 r = __builtin_convertvector(v, bfx2); return __builtin_bit_cast(unsigned, r); }
; DI f32x16 mfma32(bf16x8 a, bf16x8 b, f32x16 c) { return __builtin_amdgcn_mfma_f32_32x32x16_bf16(a, b, c, 0, 0, 0); }
; DI s16x4 tr_read(const char* p) { bfx4 r = __builtin_amdgcn_ds_read_tr16_b64_v4bf16((LDS_AS bfx4*)p); return __builtin_bit_cast(s16x4, r); }
; template <int BM, class Epi>
; DI void gemm_tile(const bf16_t* __restrict__ A, int lda, const bf16_t* __restrict__ B, int ldb, int K, int row0, int col0, const Epi& epi, char* smem) {
;     ...
;         for (int s = 0; s < 4; ++s) {
;             bf16x8 xf[MI], wf[2];
; #pragma unroll
;             for (int mi = 0; mi < MI; ++mi) xf[mi] = *(const bf16x8*)(cur + xoff + mi * 32 * GA_S + s * 32);
; #pragma unroll
;             for (int ni = 0; ni < 2; ++ni) {
;                 const char* wp = cur + woff + s * 16 * GB_S + ni * 64;
;                 wf[ni] = cat8(tr_read(wp), tr_read(wp + 4 * GB_S));
;             }
; #pragma unroll
;             for (int mi = 0; mi < MI; ++mi)
; #pragma unroll
;                 for (int ni = 0; ni < 2; ++ni) acc[mi][ni] = mfma32(wf[ni], xf[mi], acc[mi][ni]);
;             if (w1) {
;                 if (s < NA_) *(u32x4*)(nxt + aw + 64 * s * GA_S) = ra[s];
;                 *(u32x4*)(nxt + bw + 16 * s * GB_S) = rb[s];
;             }
;             if (l2) {
;                 if (s < NA_) ra[s] = *(const u32x4*)(a2 + (size_t)(64 * s) * lda);
;                 rb[s] = *(const u32x4*)(b2 + (size_t)(16 * s) * ldb);
;             }
;         }
;         __syncthreads();
;     DI void operator()(const f32x16& a0, const f32x16& a1, int row, int cbase, int hh) const {
;         const int s = row < RL ? (row >> 13) : 4;
;         const float* gp = gate + s * 9216;
;         bf16_t* yp = Y + (size_t)row * 1024;
; #pragma unroll
;         for (int ni = 0; ni < 2; ++ni)
; #pragma unroll
;             for (int q4 = 0; q4 < 4; ++q4) {
;                 const int c = cbase + ni * 32 + 8 * q4 + 4 * hh;
;                 const f32x4 g = *(const f32x4*)(gp + c);
;                 const f32x16& v = ni ? a1 : a0;
;                 u32x2 w; w.x = pk2(coef * g[0] * v[4 * q4], coef * g[1] * v[4 * q4 + 1]); w.y = pk2(coef * g[2] * v[4 * q4 + 2], coef * g[3] * v[4 * q4 + 3]);
;                 *(u32x2*)(yp + c) = w;
;             }
	v_add3_u32 v85, s1, v103, v104
	v_mfma_f32_32x32x16_bf16 v[48:63], v[76:79], v[68:71], v[48:63]
	v_mfma_f32_32x32x16_bf16 v[32:47], v[80:83], v[68:71], v[32:47]
	v_mfma_f32_32x32x16_bf16 v[16:31], v[76:79], v[72:75], v[16:31]
	v_mfma_f32_32x32x16_bf16 v[0:15], v[80:83], v[72:75], v[0:15]
	ds_read_b128 v[64:67], v84 offset:4608
	ds_read_b64_tr_b16 v[68:69], v85 offset:18432
	ds_read_b64_tr_b16 v[70:71], v85 offset:20736
	ds_read_b64_tr_b16 v[72:73], v85 offset:18496
	ds_read_b64_tr_b16 v[74:75], v85 offset:20800
	ds_read_b128 v[76:79], v84
	ds_read_b128 v[80:83], v84 offset:32
	s_waitcnt lgkmcnt(1)
	v_mfma_f32_32x32x16_bf16 v[48:63], v[68:71], v[76:79], v[48:63]
	v_mfma_f32_32x32x16_bf16 v[32:47], v[72:75], v[76:79], v[32:47]
	v_mfma_f32_32x32x16_bf16 v[16:31], v[68:71], v[64:67], v[16:31]
	v_mfma_f32_32x32x16_bf16 v[0:15], v[72:75], v[64:67], v[0:15]
	ds_read_b128 v[64:67], v84 offset:4640
	ds_read_b64_tr_b16 v[68:69], v85 offset:27648
	ds_read_b64_tr_b16 v[70:71], v85 offset:29952
	ds_read_b64_tr_b16 v[72:73], v85 offset:27712
	ds_read_b64_tr_b16 v[74:75], v85 offset:30016
	s_waitcnt lgkmcnt(2)
	v_mfma_f32_32x32x16_bf16 v[48:63], v[68:71], v[80:83], v[48:63]
	s_waitcnt lgkmcnt(0)
	v_mfma_f32_32x32x16_bf16 v[32:47], v[72:75], v[80:83], v[32:47]
	v_mfma_f32_32x32x16_bf16 v[16:31], v[68:71], v[64:67], v[16:31]
	v_mfma_f32_32x32x16_bf16 v[0:15], v[72:75], v[64:67], v[0:15]
	ds_read_b128 v[64:67], v84 offset:64
	ds_read_b128 v[68:71], v84 offset:4672
	ds_read_b64_tr_b16 v[72:73], v85 offset:36864
	ds_read_b64_tr_b16 v[74:75], v85 offset:39168
	ds_read_b64_tr_b16 v[76:77], v85 offset:36928
	ds_read_b64_tr_b16 v[78:79], v85 offset:39232
	s_waitcnt lgkmcnt(2)
	v_mfma_f32_32x32x16_bf16 v[48:63], v[72:75], v[64:67], v[48:63]
	s_waitcnt lgkmcnt(0)
	v_mfma_f32_32x32x16_bf16 v[32:47], v[76:79], v[64:67], v[32:47]
	v_mfma_f32_32x32x16_bf16 v[16:31], v[72:75], v[68:71], v[16:31]
	v_mfma_f32_32x32x16_bf16 v[0:15], v[76:79], v[68:71], v[0:15]
	ds_read_b128 v[64:67], v84 offset:96
	ds_read_b128 v[68:71], v84 offset:4704
	ds_read_b64_tr_b16 v[72:73], v85 offset:46080
	ds_read_b64_tr_b16 v[74:75], v85 offset:48384
	ds_read_b64_tr_b16 v[76:77], v85 offset:46144
	ds_read_b64_tr_b16 v[78:79], v85 offset:48448
	s_waitcnt lgkmcnt(0)
	s_barrier
	v_mfma_f32_32x32x16_bf16 v[48:63], v[72:75], v[64:67], v[48:63]
	v_mfma_f32_32x32x16_bf16 v[32:47], v[76:79], v[64:67], v[32:47]
	v_or_b32_e32 v64, s9, v99
	v_and_b32_e32 v65, 0xc0, v98
	v_add_u32_e32 v64, v64, v101
	v_lshlrev_b32_e32 v66, 2, v100
	v_mfma_f32_32x32x16_bf16 v[16:31], v[72:75], v[68:71], v[16:31]
	v_or3_b32 v74, v66, v65, s0
	v_min_i32_e32 v65, 0x8000, v64
	v_ashrrev_i32_e32 v65, 13, v65
	v_mul_i32_i24_e32 v66, 0x2400, v65
	v_ashrrev_i32_e32 v67, 31, v66
	v_ashrrev_i32_e32 v65, 31, v64
	v_readlane_b32 s0, v253, 5
	v_mfma_f32_32x32x16_bf16 v[0:15], v[76:79], v[68:71], v[0:15]
	v_ashrrev_i32_e32 v75, 31, v74
	v_lshl_add_u64 v[68:69], v[66:67], 2, s[4:5]
	v_lshlrev_b64 v[66:67], 11, v[64:65]
	v_readlane_b32 s1, v253, 6
	s_nop 1
	v_lshl_add_u64 v[76:77], s[0:1], 0, v[66:67]
	v_lshlrev_b64 v[66:67], 2, v[74:75]
	v_lshl_add_u64 v[68:69], v[68:69], 0, v[66:67]
	global_load_dwordx4 v[218:221], v[68:69], off
	global_load_dwordx4 v[222:225], v[68:69], off offset:32
	global_load_dwordx4 v[226:229], v[68:69], off offset:64
	global_load_dwordx4 v[230:233], v[68:69], off offset:96
	global_load_dwordx4 v[234:237], v[68:69], off offset:128
	global_load_dwordx4 v[238:241], v[68:69], off offset:160
	global_load_dwordx4 v[242:245], v[68:69], off offset:192
	global_load_dwordx4 v[246:249], v[68:69], off offset:224
	s_waitcnt vmcnt(0)
; DI unsigned pk2(float a, float b) { f32x2 v = {a, b}; bfx2 r = __builtin_convertvector(v, bfx2); return __builtin_bit_cast(unsigned, r); }
;     DI void operator()(const f32x16& a0, const f32x16& a1, int row, int cbase, int hh) const {
;         const int s = row < RL ? (row >> 13) : 4;
;         const float* gp = gate + s * 9216;
;         bf16_t* yp = Y + (size_t)row * 1024;
; #pragma unroll
;         for (int ni = 0; ni < 2; ++ni)
; #pragma unroll
;             for (int q4 = 0; q4 < 4; ++q4) {
;                 const int c = cbase + ni * 32 + 8 * q4 + 4 * hh;
;                 const f32x4 g = *(const f32x4*)(gp + c);
;                 const f32x16& v = ni ? a1 : a0;
;                 u32x2 w; w.x = pk2(coef * g[0] * v[4 * q4], coef * g[1] * v[4 * q4 + 1]); w.y = pk2(coef * g[2] * v[4 * q4 + 2], coef * g[3] * v[4 * q4 + 3]);
;                 *(u32x2*)(yp + c) = w;
;             }
	v_pk_mul_f32 v[70:71], v[218:219], 0.5 op_sel_hi:[1,0]
	s_nop 0
	v_pk_mul_f32 v[48:49], v[48:49], v[70:71]
	s_nop 0
	v_cvt_pk_bf16_f32 v70, v48, v49
	v_pk_mul_f32 v[48:49], v[220:221], 0.5 op_sel_hi:[1,0]
	s_nop 0
	v_pk_mul_f32 v[48:49], v[50:51], v[48:49]
	s_nop 0
	v_cvt_pk_bf16_f32 v71, v48, v49
	v_lshlrev_b64 v[48:49], 1, v[74:75]
	v_lshl_add_u64 v[74:75], v[76:77], 0, v[48:49]
	global_store_dwordx2 v[74:75], v[70:71], off
	v_pk_mul_f32 v[50:51], v[222:223], 0.5 op_sel_hi:[1,0]
	s_nop 0
	v_pk_mul_f32 v[50:51], v[52:53], v[50:51]
	v_pk_mul_f32 v[52:53], v[224:225], 0.5 op_sel_hi:[1,0]
	v_cvt_pk_bf16_f32 v50, v50, v51
	v_pk_mul_f32 v[52:53], v[54:55], v[52:53]
	s_nop 0
	v_cvt_pk_bf16_f32 v51, v52, v53
	global_store_dwordx2 v[74:75], v[50:51], off offset:16
	v_pk_mul_f32 v[50:51], v[226:227], 0.5 op_sel_hi:[1,0]
	v_pk_mul_f32 v[52:53], v[228:229], 0.5 op_sel_hi:[1,0]
	v_pk_mul_f32 v[50:51], v[56:57], v[50:51]
	v_pk_mul_f32 v[52:53], v[58:59], v[52:53]
	v_cvt_pk_bf16_f32 v50, v50, v51
	v_cvt_pk_bf16_f32 v51, v52, v53
	global_store_dwordx2 v[74:75], v[50:51], off offset:32
	v_pk_mul_f32 v[50:51], v[230:231], 0.5 op_sel_hi:[1,0]
	v_pk_mul_f32 v[52:53], v[232:233], 0.5 op_sel_hi:[1,0]
	v_pk_mul_f32 v[50:51], v[60:61], v[50:51]
	v_pk_mul_f32 v[52:53], v[62:63], v[52:53]
	v_cvt_pk_bf16_f32 v50, v50, v51
	v_cvt_pk_bf16_f32 v51, v52, v53
	global_store_dwordx2 v[74:75], v[50:51], off offset:48
	v_pk_mul_f32 v[50:51], v[234:235], 0.5 op_sel_hi:[1,0]
	s_nop 0
	v_pk_mul_f32 v[32:33], v[32:33], v[50:51]
	v_pk_mul_f32 v[50:51], v[236:237], 0.5 op_sel_hi:[1,0]
	v_cvt_pk_bf16_f32 v32, v32, v33
	v_pk_mul_f32 v[34:35], v[34:35], v[50:51]
	s_nop 0
	v_cvt_pk_bf16_f32 v33, v34, v35
	global_store_dwordx2 v[74:75], v[32:33], off offset:64
	v_pk_mul_f32 v[32:33], v[238:239], 0.5 op_sel_hi:[1,0]
	v_pk_mul_f32 v[34:35], v[240:241], 0.5 op_sel_hi:[1,0]
	v_pk_mul_f32 v[32:33], v[36:37], v[32:33]
	v_pk_mul_f32 v[34:35], v[38:39], v[34:35]
	v_cvt_pk_bf16_f32 v32, v32, v33
	v_cvt_pk_bf16_f32 v33, v34, v35
	global_store_dwordx2 v[74:75], v[32:33], off offset:80
	v_pk_mul_f32 v[32:33], v[242:243], 0.5 op_sel_hi:[1,0]
	v_pk_mul_f32 v[34:35], v[244:245], 0.5 op_sel_hi:[1,0]
	v_pk_mul_f32 v[32:33], v[40:41], v[32:33]
	v_pk_mul_f32 v[34:35], v[42:43], v[34:35]
	v_cvt_pk_bf16_f32 v32, v32, v33
	v_cvt_pk_bf16_f32 v33, v34, v35
	global_store_dwordx2 v[74:75], v[32:33], off offset:96
	v_pk_mul_f32 v[32:33], v[246:247], 0.5 op_sel_hi:[1,0]
	v_pk_mul_f32 v[34:35], v[248:249], 0.5 op_sel_hi:[1,0]
	v_pk_mul_f32 v[32:33], v[44:45], v[32:33]
	v_pk_mul_f32 v[34:35], v[46:47], v[34:35]
	v_cvt_pk_bf16_f32 v32, v32, v33
	v_cvt_pk_bf16_f32 v33, v34, v35
	global_store_dwordx2 v[74:75], v[32:33], off offset:112
	v_or_b32_e32 v32, 32, v64
	v_min_i32_e32 v33, 0x8000, v32
	v_ashrrev_i32_e32 v33, 13, v33
	v_mul_i32_i24_e32 v34, 0x2400, v33
	v_ashrrev_i32_e32 v35, 31, v34
	v_ashrrev_i32_e32 v33, 31, v32
	v_lshl_add_u64 v[34:35], v[34:35], 2, s[4:5]
	v_lshlrev_b64 v[32:33], 11, v[32:33]
	v_lshl_add_u64 v[38:39], s[0:1], 0, v[32:33]
	v_lshl_add_u64 v[32:33], v[34:35], 0, v[66:67]
	global_load_dwordx4 v[218:221], v[32:33], off
	global_load_dwordx4 v[222:225], v[32:33], off offset:32
	global_load_dwordx4 v[226:229], v[32:33], off offset:64
	global_load_dwordx4 v[230:233], v[32:33], off offset:96
	global_load_dwordx4 v[234:237], v[32:33], off offset:128
	global_load_dwordx4 v[238:241], v[32:33], off offset:160
	global_load_dwordx4 v[242:245], v[32:33], off offset:192
	global_load_dwordx4 v[246:249], v[32:33], off offset:224
	s_waitcnt vmcnt(0)
	v_pk_mul_f32 v[34:35], v[218:219], 0.5 op_sel_hi:[1,0]
	s_nop 0
	v_pk_mul_f32 v[16:17], v[16:17], v[34:35]
	v_pk_mul_f32 v[34:35], v[220:221], 0.5 op_sel_hi:[1,0]
	v_cvt_pk_bf16_f32 v16, v16, v17
	v_pk_mul_f32 v[18:19], v[18:19], v[34:35]
	v_lshl_add_u64 v[34:35], v[38:39], 0, v[48:49]
	v_cvt_pk_bf16_f32 v17, v18, v19
	global_store_dwordx2 v[34:35], v[16:17], off
	v_pk_mul_f32 v[16:17], v[222:223], 0.5 op_sel_hi:[1,0]
	v_pk_mul_f32 v[18:19], v[224:225], 0.5 op_sel_hi:[1,0]
	v_pk_mul_f32 v[16:17], v[20:21], v[16:17]
	v_pk_mul_f32 v[18:19], v[22:23], v[18:19]
	v_cvt_pk_bf16_f32 v16, v16, v17
	v_cvt_pk_bf16_f32 v17, v18, v19
	global_store_dwordx2 v[34:35], v[16:17], off offset:16
	v_pk_mul_f32 v[16:17], v[226:227], 0.5 op_sel_hi:[1,0]
	v_pk_mul_f32 v[18:19], v[228:229], 0.5 op_sel_hi:[1,0]
	v_pk_mul_f32 v[16:17], v[24:25], v[16:17]
	v_pk_mul_f32 v[18:19], v[26:27], v[18:19]
	v_cvt_pk_bf16_f32 v16, v16, v17
	v_cvt_pk_bf16_f32 v17, v18, v19
	global_store_dwordx2 v[34:35], v[16:17], off offset:32
	v_pk_mul_f32 v[16:17], v[230:231], 0.5 op_sel_hi:[1,0]
	v_pk_mul_f32 v[18:19], v[232:233], 0.5 op_sel_hi:[1,0]
	v_pk_mul_f32 v[16:17], v[28:29], v[16:17]
	v_pk_mul_f32 v[18:19], v[30:31], v[18:19]
	v_cvt_pk_bf16_f32 v16, v16, v17
	v_cvt_pk_bf16_f32 v17, v18, v19
	global_store_dwordx2 v[34:35], v[16:17], off offset:48
	v_pk_mul_f32 v[16:17], v[234:235], 0.5 op_sel_hi:[1,0]
	s_nop 0
	v_pk_mul_f32 v[0:1], v[0:1], v[16:17]
	v_pk_mul_f32 v[16:17], v[236:237], 0.5 op_sel_hi:[1,0]
	v_cvt_pk_bf16_f32 v0, v0, v1
	v_pk_mul_f32 v[2:3], v[2:3], v[16:17]
	s_nop 0
	v_cvt_pk_bf16_f32 v1, v2, v3
	global_store_dwordx2 v[34:35], v[0:1], off offset:64
	v_pk_mul_f32 v[0:1], v[238:239], 0.5 op_sel_hi:[1,0]
	v_pk_mul_f32 v[2:3], v[240:241], 0.5 op_sel_hi:[1,0]
	v_pk_mul_f32 v[0:1], v[4:5], v[0:1]
	v_pk_mul_f32 v[2:3], v[6:7], v[2:3]
	v_cvt_pk_bf16_f32 v0, v0, v1
	v_cvt_pk_bf16_f32 v1, v2, v3
	global_store_dwordx2 v[34:35], v[0:1], off offset:80
	v_pk_mul_f32 v[0:1], v[242:243], 0.5 op_sel_hi:[1,0]
	v_pk_mul_f32 v[2:3], v[244:245], 0.5 op_sel_hi:[1,0]
	v_pk_mul_f32 v[0:1], v[8:9], v[0:1]
	v_pk_mul_f32 v[2:3], v[10:11], v[2:3]
	v_cvt_pk_bf16_f32 v0, v0, v1
	v_cvt_pk_bf16_f32 v1, v2, v3
	global_store_dwordx2 v[34:35], v[0:1], off offset:96
	v_pk_mul_f32 v[0:1], v[246:247], 0.5 op_sel_hi:[1,0]
	v_pk_mul_f32 v[2:3], v[248:249], 0.5 op_sel_hi:[1,0]
	v_pk_mul_f32 v[0:1], v[12:13], v[0:1]
	v_pk_mul_f32 v[2:3], v[14:15], v[2:3]
	v_cvt_pk_bf16_f32 v0, v0, v1
	v_cvt_pk_bf16_f32 v1, v2, v3
	global_store_dwordx2 v[34:35], v[0:1], off offset:112
	s_cbranch_scc0 .LBB0_1491
